# GDN scan: one static s_setprio 1 for waves 4-7 (younger half) for the duration of the scan
# speedup vs baseline: 1.0047x; 1.0047x over previous
; DI int otid() { int t = threadIdx.x; asm volatile("" : "+v"(t)); return t; }
; DI void gdn_scan_item(const P& p, int item, unsigned char* smem) {
;     const int seq = (item & 7) * 4 + (item >> 5), cq = (item >> 3) & 3;
;     const int dir = seq >> 4, b = (seq >> 2) & 3, h = seq & 3;
;     constexpr int BUFB = 3 * 17408 + 9216 + 5120;
;     bf16_t* sVN = (bf16_t*)(smem + 2 * BUFB);
;     float* sdec = (float*)(smem + 2 * BUFB + 5120);
;     const bf16_t* U = (const bf16_t*)(p.ws + WS_GDN_U); const bf16_t* W = (const bf16_t*)(p.ws + WS_GDN_W); const bf16_t* QI = (const bf16_t*)(p.ws + WS_GDN_QI); const bf16_t* KO = (const bf16_t*)(p.ws + WS_GDN_KO);
;     const bf16_t* AT = (const bf16_t*)(p.ws + WS_GDN_AT); const float* DC = (const float*)(p.ws + WS_GDN_DC);
;     bf16_t* OG = (bf16_t*)(p.ws + WS_NBUF) + (size_t)(2 + dir) * NROW * 512;
;     const int tid = otid(), w = tid >> 6, lane = tid & 63, l15 = lane & 15, g = lane >> 4, q4 = l15 >> 2, p4 = l15 & 3;
;     const int mt = w >> 1, nt = w & 1;
.LBB0_489:
	v_readfirstlane_b32 s98, v166
	s_nop 0
	s_lshr_b32 s98, s98, 6
	s_cmp_ge_u32 s98, 4
	s_cbranch_scc0 .Lgdn_prio_done
	s_setprio 1

; DI void gdn_scan_item(const P& p, int item, unsigned char* smem) {
;     ...
;     __syncthreads();
.LBB0_640:
	s_setprio 0
	s_mov_b64 s[0:1], -1
	s_waitcnt lgkmcnt(0)
	s_barrier
	s_and_b64 vcc, exec, s[36:37]
	s_cbranch_vccz .LBB0_475
	s_branch .LBB0_529
